# EpiResid epilogue de-serialised: 32 residual loads in flight, counted vmcnt(31) instead of load-wait0-store ladder
# speedup vs baseline: 1.0150x; 1.0150x over previous
; DI float bflo(unsigned w) { return __uint_as_float(w << 16); }
; DI float bfhi(unsigned w) { return __uint_as_float(w & 0xffff0000u); }
;     DI void operator()(const f32x4 (&acc)[2][2][4][2], const pg8::Unit& u, int wr, int wc, int fr, int fq) const {
;         const int row0 = u.pm * 256 + wr * 64 + fr, col0 = u.pn * 256 + wc * 32 + 4 * fq;
;         const bf16_t* XBr = (const bf16_t*)((const unsigned char*)R + (WS_XB - WS_R));
;         if (u.split) {
;             float* P0 = PART + ((size_t)(u.kt0 / u.nt) * 256 + (wr * 64 + fr)) * DM + col0;
; #pragma unroll
;             for (int ai = 0; ai < 2; ++ai)
; #pragma unroll
;                 for (int m = 0; m < 4; ++m) { float* rowp = P0 + (size_t)(ai * 128 + m * 16) * DM;
; #pragma unroll
;                     for (int bj = 0; bj < 2; ++bj)
; #pragma unroll
;                         for (int n = 0; n < 2; ++n) *(f32x4*)(rowp + bj * 128 + n * 16) = acc[ai][bj][m][n] * scale; }
;             return; }
; #pragma unroll
;         for (int ai = 0; ai < 2; ++ai)
; #pragma unroll
;             for (int m = 0; m < 4; ++m) { float* rowp = R + (size_t)(row0 + ai * 128 + m * 16) * DM + col0;
; #pragma unroll
;                 for (int bj = 0; bj < 2; ++bj)
; #pragma unroll
;                     for (int n = 0; n < 2; ++n) { const u32x2 hb = *(const u32x2*)(XBr + (size_t)(row0 + ai * 128 + m * 16) * DM + col0 + bj * 128 + n * 16);
;                         const f32x4 r = (f32x4){bflo(hb.x), bfhi(hb.x), bflo(hb.y), bfhi(hb.y)} * ALPHA; *(f32x4*)(rowp + bj * 128 + n * 16) = r + acc[ai][bj][m][n] * scale; }
;                 if (m & 1) asm volatile("" ::: "memory"); }
.LBB0_804:
	v_lshl_add_u32 v150, s91, 8, v136
	v_ashrrev_i32_e32 v151, 31, v150
	v_lshl_add_u64 v[148:149], v[146:147], 1, s[96:97]
	v_lshlrev_b64 v[180:181], 11, v[150:151]
	v_lshl_add_u64 v[180:181], v[148:149], 0, v[180:181]
	v_lshlrev_b64 v[184:185], 12, v[150:151]
	v_lshlrev_b64 v[146:147], 2, v[146:147]
	v_mov_b32_e32 v135, v134
	v_lshl_add_u64 v[184:185], s[68:69], 0, v[184:185]
	v_lshl_add_u64 v[184:185], v[184:185], 0, v[146:147]
	global_load_dwordx2 v[188:189], v[180:181], off
	global_load_dwordx2 v[190:191], v[180:181], off offset:32
	global_load_dwordx2 v[192:193], v[180:181], off offset:256
	global_load_dwordx2 v[194:195], v[180:181], off offset:288
	s_mov_b64 s[16:17], 0x8000
	v_lshl_add_u64 v[182:183], v[180:181], 0, s[16:17]
	global_load_dwordx2 v[196:197], v[182:183], off
	global_load_dwordx2 v[198:199], v[182:183], off offset:32
	global_load_dwordx2 v[200:201], v[182:183], off offset:256
	global_load_dwordx2 v[202:203], v[182:183], off offset:288
	s_mov_b64 s[16:17], 0x10000
	v_lshl_add_u64 v[186:187], v[180:181], 0, s[16:17]
	global_load_dwordx2 v[204:205], v[186:187], off
	global_load_dwordx2 v[206:207], v[186:187], off offset:32
	global_load_dwordx2 v[208:209], v[186:187], off offset:256
	global_load_dwordx2 v[210:211], v[186:187], off offset:288
	s_mov_b64 s[16:17], 0x18000
	v_lshl_add_u64 v[182:183], v[180:181], 0, s[16:17]
	global_load_dwordx2 v[212:213], v[182:183], off
	global_load_dwordx2 v[214:215], v[182:183], off offset:32
	global_load_dwordx2 v[216:217], v[182:183], off offset:256
	global_load_dwordx2 v[218:219], v[182:183], off offset:288
	s_mov_b64 s[16:17], 0x40000
	v_lshl_add_u64 v[186:187], v[180:181], 0, s[16:17]
	global_load_dwordx2 v[220:221], v[186:187], off
	global_load_dwordx2 v[222:223], v[186:187], off offset:32
	global_load_dwordx2 v[224:225], v[186:187], off offset:256
	global_load_dwordx2 v[226:227], v[186:187], off offset:288
	s_mov_b64 s[16:17], 0x48000
	v_lshl_add_u64 v[182:183], v[180:181], 0, s[16:17]
	global_load_dwordx2 v[228:229], v[182:183], off
	global_load_dwordx2 v[230:231], v[182:183], off offset:32
	global_load_dwordx2 v[232:233], v[182:183], off offset:256
	global_load_dwordx2 v[234:235], v[182:183], off offset:288
	s_mov_b64 s[16:17], 0x50000
	v_lshl_add_u64 v[186:187], v[180:181], 0, s[16:17]
	global_load_dwordx2 v[236:237], v[186:187], off
	global_load_dwordx2 v[238:239], v[186:187], off offset:32
	global_load_dwordx2 v[240:241], v[186:187], off offset:256
	global_load_dwordx2 v[242:243], v[186:187], off offset:288
	s_mov_b64 s[16:17], 0x58000
	v_lshl_add_u64 v[182:183], v[180:181], 0, s[16:17]
	global_load_dwordx2 v[244:245], v[182:183], off
	global_load_dwordx2 v[246:247], v[182:183], off offset:32
	global_load_dwordx2 v[248:249], v[182:183], off offset:256
	global_load_dwordx2 v[250:251], v[182:183], off offset:288
	s_waitcnt vmcnt(31)
	v_lshlrev_b32_e32 v148, 16, v188
	v_and_b32_e32 v149, 0xffff0000, v188
	v_lshlrev_b32_e32 v188, 16, v189
	v_and_b32_e32 v189, 0xffff0000, v189
	v_pk_mul_f32 v[148:149], v[148:149], s[90:91] op_sel_hi:[1,0]
	v_pk_mul_f32 v[188:189], v[188:189], s[90:91] op_sel_hi:[1,0]
	v_pk_fma_f32 v[124:125], v[140:141], v[124:125], v[148:149]
	v_pk_fma_f32 v[126:127], v[134:135], v[126:127], v[188:189]
	global_store_dwordx4 v[184:185], v[124:127], off
	s_waitcnt vmcnt(31)
	v_lshlrev_b32_e32 v150, 16, v190
	v_and_b32_e32 v151, 0xffff0000, v190
	v_lshlrev_b32_e32 v190, 16, v191
	v_and_b32_e32 v191, 0xffff0000, v191
	v_pk_mul_f32 v[150:151], v[150:151], s[90:91] op_sel_hi:[1,0]
	v_pk_mul_f32 v[190:191], v[190:191], s[90:91] op_sel_hi:[1,0]
	v_pk_fma_f32 v[120:121], v[140:141], v[120:121], v[150:151]
	v_pk_fma_f32 v[122:123], v[134:135], v[122:123], v[190:191]
	global_store_dwordx4 v[184:185], v[120:123], off offset:64
	s_waitcnt vmcnt(31)
	v_lshlrev_b32_e32 v148, 16, v192
	v_and_b32_e32 v149, 0xffff0000, v192
	v_lshlrev_b32_e32 v192, 16, v193
	v_and_b32_e32 v193, 0xffff0000, v193
	v_pk_mul_f32 v[148:149], v[148:149], s[90:91] op_sel_hi:[1,0]
	v_pk_mul_f32 v[192:193], v[192:193], s[90:91] op_sel_hi:[1,0]
	v_pk_fma_f32 v[116:117], v[140:141], v[116:117], v[148:149]
	v_pk_fma_f32 v[118:119], v[134:135], v[118:119], v[192:193]
	global_store_dwordx4 v[184:185], v[116:119], off offset:512
	s_waitcnt vmcnt(31)
	v_lshlrev_b32_e32 v150, 16, v194
	v_and_b32_e32 v151, 0xffff0000, v194
	v_lshlrev_b32_e32 v194, 16, v195
	v_and_b32_e32 v195, 0xffff0000, v195
	v_pk_mul_f32 v[150:151], v[150:151], s[90:91] op_sel_hi:[1,0]
	v_pk_mul_f32 v[194:195], v[194:195], s[90:91] op_sel_hi:[1,0]
	v_pk_fma_f32 v[108:109], v[140:141], v[108:109], v[150:151]
	v_pk_fma_f32 v[110:111], v[134:135], v[110:111], v[194:195]
	global_store_dwordx4 v[184:185], v[108:111], off offset:576
	s_mov_b64 s[16:17], 0x10000
	v_lshl_add_u64 v[182:183], v[184:185], 0, s[16:17]
	s_waitcnt vmcnt(31)
	v_lshlrev_b32_e32 v148, 16, v196
	v_and_b32_e32 v149, 0xffff0000, v196
	v_lshlrev_b32_e32 v196, 16, v197
	v_and_b32_e32 v197, 0xffff0000, v197
	v_pk_mul_f32 v[148:149], v[148:149], s[90:91] op_sel_hi:[1,0]
	v_pk_mul_f32 v[196:197], v[196:197], s[90:91] op_sel_hi:[1,0]
	v_pk_fma_f32 v[112:113], v[140:141], v[112:113], v[148:149]
	v_pk_fma_f32 v[114:115], v[134:135], v[114:115], v[196:197]
	global_store_dwordx4 v[182:183], v[112:115], off
	s_waitcnt vmcnt(31)
	v_lshlrev_b32_e32 v150, 16, v198
	v_and_b32_e32 v151, 0xffff0000, v198
	v_lshlrev_b32_e32 v198, 16, v199
	v_and_b32_e32 v199, 0xffff0000, v199
	v_pk_mul_f32 v[150:151], v[150:151], s[90:91] op_sel_hi:[1,0]
	v_pk_mul_f32 v[198:199], v[198:199], s[90:91] op_sel_hi:[1,0]
	v_pk_fma_f32 v[104:105], v[140:141], v[104:105], v[150:151]
	v_pk_fma_f32 v[106:107], v[134:135], v[106:107], v[198:199]
	global_store_dwordx4 v[182:183], v[104:107], off offset:64
	s_waitcnt vmcnt(31)
; DI float bflo(unsigned w) { return __uint_as_float(w << 16); }
; DI float bfhi(unsigned w) { return __uint_as_float(w & 0xffff0000u); }
;     DI void operator()(const f32x4 (&acc)[2][2][4][2], const pg8::Unit& u, int wr, int wc, int fr, int fq) const {
;     ...
; #pragma unroll
;         for (int ai = 0; ai < 2; ++ai)
; #pragma unroll
;             for (int m = 0; m < 4; ++m) { float* rowp = R + (size_t)(row0 + ai * 128 + m * 16) * DM + col0;
; #pragma unroll
;                 for (int bj = 0; bj < 2; ++bj)
; #pragma unroll
;                     for (int n = 0; n < 2; ++n) { const u32x2 hb = *(const u32x2*)(XBr + (size_t)(row0 + ai * 128 + m * 16) * DM + col0 + bj * 128 + n * 16);
;                         const f32x4 r = (f32x4){bflo(hb.x), bfhi(hb.x), bflo(hb.y), bfhi(hb.y)} * ALPHA; *(f32x4*)(rowp + bj * 128 + n * 16) = r + acc[ai][bj][m][n] * scale; }
;                 if (m & 1) asm volatile("" ::: "memory"); }
	v_lshlrev_b32_e32 v148, 16, v200
	v_and_b32_e32 v149, 0xffff0000, v200
	v_lshlrev_b32_e32 v200, 16, v201
	v_and_b32_e32 v201, 0xffff0000, v201
	v_pk_mul_f32 v[148:149], v[148:149], s[90:91] op_sel_hi:[1,0]
	v_pk_mul_f32 v[200:201], v[200:201], s[90:91] op_sel_hi:[1,0]
	v_pk_fma_f32 v[100:101], v[140:141], v[100:101], v[148:149]
	v_pk_fma_f32 v[102:103], v[134:135], v[102:103], v[200:201]
	global_store_dwordx4 v[182:183], v[100:103], off offset:512
	s_waitcnt vmcnt(31)
	v_lshlrev_b32_e32 v150, 16, v202
	v_and_b32_e32 v151, 0xffff0000, v202
	v_lshlrev_b32_e32 v202, 16, v203
	v_and_b32_e32 v203, 0xffff0000, v203
	v_pk_mul_f32 v[150:151], v[150:151], s[90:91] op_sel_hi:[1,0]
	v_pk_mul_f32 v[202:203], v[202:203], s[90:91] op_sel_hi:[1,0]
	v_pk_fma_f32 v[92:93], v[140:141], v[92:93], v[150:151]
	v_pk_fma_f32 v[94:95], v[134:135], v[94:95], v[202:203]
	global_store_dwordx4 v[182:183], v[92:95], off offset:576
	s_mov_b64 s[16:17], 0x20000
	v_lshl_add_u64 v[186:187], v[184:185], 0, s[16:17]
	s_waitcnt vmcnt(31)
	v_lshlrev_b32_e32 v148, 16, v204
	v_and_b32_e32 v149, 0xffff0000, v204
	v_lshlrev_b32_e32 v204, 16, v205
	v_and_b32_e32 v205, 0xffff0000, v205
	v_pk_mul_f32 v[148:149], v[148:149], s[90:91] op_sel_hi:[1,0]
	v_pk_mul_f32 v[204:205], v[204:205], s[90:91] op_sel_hi:[1,0]
	v_pk_fma_f32 v[96:97], v[140:141], v[96:97], v[148:149]
	v_pk_fma_f32 v[98:99], v[134:135], v[98:99], v[204:205]
	global_store_dwordx4 v[186:187], v[96:99], off
	s_waitcnt vmcnt(31)
	v_lshlrev_b32_e32 v150, 16, v206
	v_and_b32_e32 v151, 0xffff0000, v206
	v_lshlrev_b32_e32 v206, 16, v207
	v_and_b32_e32 v207, 0xffff0000, v207
	v_pk_mul_f32 v[150:151], v[150:151], s[90:91] op_sel_hi:[1,0]
	v_pk_mul_f32 v[206:207], v[206:207], s[90:91] op_sel_hi:[1,0]
	v_pk_fma_f32 v[88:89], v[140:141], v[88:89], v[150:151]
	v_pk_fma_f32 v[90:91], v[134:135], v[90:91], v[206:207]
	global_store_dwordx4 v[186:187], v[88:91], off offset:64
	s_waitcnt vmcnt(31)
	v_lshlrev_b32_e32 v148, 16, v208
	v_and_b32_e32 v149, 0xffff0000, v208
	v_lshlrev_b32_e32 v208, 16, v209
	v_and_b32_e32 v209, 0xffff0000, v209
	v_pk_mul_f32 v[148:149], v[148:149], s[90:91] op_sel_hi:[1,0]
	v_pk_mul_f32 v[208:209], v[208:209], s[90:91] op_sel_hi:[1,0]
	v_pk_fma_f32 v[84:85], v[140:141], v[84:85], v[148:149]
	v_pk_fma_f32 v[86:87], v[134:135], v[86:87], v[208:209]
	global_store_dwordx4 v[186:187], v[84:87], off offset:512
	s_waitcnt vmcnt(31)
	v_lshlrev_b32_e32 v150, 16, v210
	v_and_b32_e32 v151, 0xffff0000, v210
	v_lshlrev_b32_e32 v210, 16, v211
	v_and_b32_e32 v211, 0xffff0000, v211
	v_pk_mul_f32 v[150:151], v[150:151], s[90:91] op_sel_hi:[1,0]
	v_pk_mul_f32 v[210:211], v[210:211], s[90:91] op_sel_hi:[1,0]
	v_pk_fma_f32 v[76:77], v[140:141], v[76:77], v[150:151]
	v_pk_fma_f32 v[78:79], v[134:135], v[78:79], v[210:211]
	global_store_dwordx4 v[186:187], v[76:79], off offset:576
	s_mov_b64 s[16:17], 0x30000
	v_lshl_add_u64 v[182:183], v[184:185], 0, s[16:17]
	s_waitcnt vmcnt(31)
	v_lshlrev_b32_e32 v148, 16, v212
	v_and_b32_e32 v149, 0xffff0000, v212
	v_lshlrev_b32_e32 v212, 16, v213
	v_and_b32_e32 v213, 0xffff0000, v213
	v_pk_mul_f32 v[148:149], v[148:149], s[90:91] op_sel_hi:[1,0]
	v_pk_mul_f32 v[212:213], v[212:213], s[90:91] op_sel_hi:[1,0]
	v_pk_fma_f32 v[80:81], v[140:141], v[80:81], v[148:149]
	v_pk_fma_f32 v[82:83], v[134:135], v[82:83], v[212:213]
	global_store_dwordx4 v[182:183], v[80:83], off
	s_waitcnt vmcnt(31)
	v_lshlrev_b32_e32 v150, 16, v214
	v_and_b32_e32 v151, 0xffff0000, v214
	v_lshlrev_b32_e32 v214, 16, v215
	v_and_b32_e32 v215, 0xffff0000, v215
	v_pk_mul_f32 v[150:151], v[150:151], s[90:91] op_sel_hi:[1,0]
	v_pk_mul_f32 v[214:215], v[214:215], s[90:91] op_sel_hi:[1,0]
	v_pk_fma_f32 v[72:73], v[140:141], v[72:73], v[150:151]
	v_pk_fma_f32 v[74:75], v[134:135], v[74:75], v[214:215]
	global_store_dwordx4 v[182:183], v[72:75], off offset:64
	s_waitcnt vmcnt(31)
	v_lshlrev_b32_e32 v148, 16, v216
	v_and_b32_e32 v149, 0xffff0000, v216
	v_lshlrev_b32_e32 v216, 16, v217
	v_and_b32_e32 v217, 0xffff0000, v217
	v_pk_mul_f32 v[148:149], v[148:149], s[90:91] op_sel_hi:[1,0]
	v_pk_mul_f32 v[216:217], v[216:217], s[90:91] op_sel_hi:[1,0]
	v_pk_fma_f32 v[68:69], v[140:141], v[68:69], v[148:149]
	v_pk_fma_f32 v[70:71], v[134:135], v[70:71], v[216:217]
	global_store_dwordx4 v[182:183], v[68:71], off offset:512
	s_waitcnt vmcnt(31)
	v_lshlrev_b32_e32 v150, 16, v218
	v_and_b32_e32 v151, 0xffff0000, v218
	v_lshlrev_b32_e32 v218, 16, v219
	v_and_b32_e32 v219, 0xffff0000, v219
	v_pk_mul_f32 v[150:151], v[150:151], s[90:91] op_sel_hi:[1,0]
	v_pk_mul_f32 v[218:219], v[218:219], s[90:91] op_sel_hi:[1,0]
	v_pk_fma_f32 v[64:65], v[140:141], v[64:65], v[150:151]
	v_pk_fma_f32 v[66:67], v[134:135], v[66:67], v[218:219]
	global_store_dwordx4 v[182:183], v[64:67], off offset:576
	s_mov_b64 s[16:17], 0x80000
	v_lshl_add_u64 v[186:187], v[184:185], 0, s[16:17]
	s_waitcnt vmcnt(31)
	v_lshlrev_b32_e32 v148, 16, v220
	v_and_b32_e32 v149, 0xffff0000, v220
	v_lshlrev_b32_e32 v220, 16, v221
	v_and_b32_e32 v221, 0xffff0000, v221
	v_pk_mul_f32 v[148:149], v[148:149], s[90:91] op_sel_hi:[1,0]
	v_pk_mul_f32 v[220:221], v[220:221], s[90:91] op_sel_hi:[1,0]
	v_pk_fma_f32 v[60:61], v[140:141], v[60:61], v[148:149]
	v_pk_fma_f32 v[62:63], v[134:135], v[62:63], v[220:221]
	global_store_dwordx4 v[186:187], v[60:63], off
	s_waitcnt vmcnt(31)
	v_lshlrev_b32_e32 v150, 16, v222
	v_and_b32_e32 v151, 0xffff0000, v222
	v_lshlrev_b32_e32 v222, 16, v223
	v_and_b32_e32 v223, 0xffff0000, v223
	v_pk_mul_f32 v[150:151], v[150:151], s[90:91] op_sel_hi:[1,0]
	v_pk_mul_f32 v[222:223], v[222:223], s[90:91] op_sel_hi:[1,0]
	v_pk_fma_f32 v[56:57], v[140:141], v[56:57], v[150:151]
	v_pk_fma_f32 v[58:59], v[134:135], v[58:59], v[222:223]
	global_store_dwordx4 v[186:187], v[56:59], off offset:64
	s_waitcnt vmcnt(31)
; DI float bflo(unsigned w) { return __uint_as_float(w << 16); }
; DI float bfhi(unsigned w) { return __uint_as_float(w & 0xffff0000u); }
;     DI void operator()(const f32x4 (&acc)[2][2][4][2], const pg8::Unit& u, int wr, int wc, int fr, int fq) const {
;     ...
; #pragma unroll
;         for (int ai = 0; ai < 2; ++ai)
; #pragma unroll
;             for (int m = 0; m < 4; ++m) { float* rowp = R + (size_t)(row0 + ai * 128 + m * 16) * DM + col0;
; #pragma unroll
;                 for (int bj = 0; bj < 2; ++bj)
; #pragma unroll
;                     for (int n = 0; n < 2; ++n) { const u32x2 hb = *(const u32x2*)(XBr + (size_t)(row0 + ai * 128 + m * 16) * DM + col0 + bj * 128 + n * 16);
;                         const f32x4 r = (f32x4){bflo(hb.x), bfhi(hb.x), bflo(hb.y), bfhi(hb.y)} * ALPHA; *(f32x4*)(rowp + bj * 128 + n * 16) = r + acc[ai][bj][m][n] * scale; }
;                 if (m & 1) asm volatile("" ::: "memory"); }
	v_lshlrev_b32_e32 v148, 16, v224
	v_and_b32_e32 v149, 0xffff0000, v224
	v_lshlrev_b32_e32 v224, 16, v225
	v_and_b32_e32 v225, 0xffff0000, v225
	v_pk_mul_f32 v[148:149], v[148:149], s[90:91] op_sel_hi:[1,0]
	v_pk_mul_f32 v[224:225], v[224:225], s[90:91] op_sel_hi:[1,0]
	v_pk_fma_f32 v[52:53], v[140:141], v[52:53], v[148:149]
	v_pk_fma_f32 v[54:55], v[134:135], v[54:55], v[224:225]
	global_store_dwordx4 v[186:187], v[52:55], off offset:512
	s_waitcnt vmcnt(31)
	v_lshlrev_b32_e32 v150, 16, v226
	v_and_b32_e32 v151, 0xffff0000, v226
	v_lshlrev_b32_e32 v226, 16, v227
	v_and_b32_e32 v227, 0xffff0000, v227
	v_pk_mul_f32 v[150:151], v[150:151], s[90:91] op_sel_hi:[1,0]
	v_pk_mul_f32 v[226:227], v[226:227], s[90:91] op_sel_hi:[1,0]
	v_pk_fma_f32 v[44:45], v[140:141], v[44:45], v[150:151]
	v_pk_fma_f32 v[46:47], v[134:135], v[46:47], v[226:227]
	global_store_dwordx4 v[186:187], v[44:47], off offset:576
	s_mov_b64 s[16:17], 0x90000
	v_lshl_add_u64 v[182:183], v[184:185], 0, s[16:17]
	s_waitcnt vmcnt(31)
	v_lshlrev_b32_e32 v148, 16, v228
	v_and_b32_e32 v149, 0xffff0000, v228
	v_lshlrev_b32_e32 v228, 16, v229
	v_and_b32_e32 v229, 0xffff0000, v229
	v_pk_mul_f32 v[148:149], v[148:149], s[90:91] op_sel_hi:[1,0]
	v_pk_mul_f32 v[228:229], v[228:229], s[90:91] op_sel_hi:[1,0]
	v_pk_fma_f32 v[48:49], v[140:141], v[48:49], v[148:149]
	v_pk_fma_f32 v[50:51], v[134:135], v[50:51], v[228:229]
	global_store_dwordx4 v[182:183], v[48:51], off
	s_waitcnt vmcnt(31)
	v_lshlrev_b32_e32 v150, 16, v230
	v_and_b32_e32 v151, 0xffff0000, v230
	v_lshlrev_b32_e32 v230, 16, v231
	v_and_b32_e32 v231, 0xffff0000, v231
	v_pk_mul_f32 v[150:151], v[150:151], s[90:91] op_sel_hi:[1,0]
	v_pk_mul_f32 v[230:231], v[230:231], s[90:91] op_sel_hi:[1,0]
	v_pk_fma_f32 v[40:41], v[140:141], v[40:41], v[150:151]
	v_pk_fma_f32 v[42:43], v[134:135], v[42:43], v[230:231]
	global_store_dwordx4 v[182:183], v[40:43], off offset:64
	s_waitcnt vmcnt(31)
	v_lshlrev_b32_e32 v148, 16, v232
	v_and_b32_e32 v149, 0xffff0000, v232
	v_lshlrev_b32_e32 v232, 16, v233
	v_and_b32_e32 v233, 0xffff0000, v233
	v_pk_mul_f32 v[148:149], v[148:149], s[90:91] op_sel_hi:[1,0]
	v_pk_mul_f32 v[232:233], v[232:233], s[90:91] op_sel_hi:[1,0]
	v_pk_fma_f32 v[36:37], v[140:141], v[36:37], v[148:149]
	v_pk_fma_f32 v[38:39], v[134:135], v[38:39], v[232:233]
	global_store_dwordx4 v[182:183], v[36:39], off offset:512
	s_waitcnt vmcnt(31)
	v_lshlrev_b32_e32 v150, 16, v234
	v_and_b32_e32 v151, 0xffff0000, v234
	v_lshlrev_b32_e32 v234, 16, v235
	v_and_b32_e32 v235, 0xffff0000, v235
	v_pk_mul_f32 v[150:151], v[150:151], s[90:91] op_sel_hi:[1,0]
	v_pk_mul_f32 v[234:235], v[234:235], s[90:91] op_sel_hi:[1,0]
	v_pk_fma_f32 v[28:29], v[140:141], v[28:29], v[150:151]
	v_pk_fma_f32 v[30:31], v[134:135], v[30:31], v[234:235]
	global_store_dwordx4 v[182:183], v[28:31], off offset:576
	s_mov_b64 s[16:17], 0xa0000
	v_lshl_add_u64 v[186:187], v[184:185], 0, s[16:17]
	s_waitcnt vmcnt(31)
	v_lshlrev_b32_e32 v148, 16, v236
	v_and_b32_e32 v149, 0xffff0000, v236
	v_lshlrev_b32_e32 v236, 16, v237
	v_and_b32_e32 v237, 0xffff0000, v237
	v_pk_mul_f32 v[148:149], v[148:149], s[90:91] op_sel_hi:[1,0]
	v_pk_mul_f32 v[236:237], v[236:237], s[90:91] op_sel_hi:[1,0]
	v_pk_fma_f32 v[32:33], v[140:141], v[32:33], v[148:149]
	v_pk_fma_f32 v[34:35], v[134:135], v[34:35], v[236:237]
	global_store_dwordx4 v[186:187], v[32:35], off
	s_waitcnt vmcnt(31)
	v_lshlrev_b32_e32 v150, 16, v238
	v_and_b32_e32 v151, 0xffff0000, v238
	v_lshlrev_b32_e32 v238, 16, v239
	v_and_b32_e32 v239, 0xffff0000, v239
	v_pk_mul_f32 v[150:151], v[150:151], s[90:91] op_sel_hi:[1,0]
	v_pk_mul_f32 v[238:239], v[238:239], s[90:91] op_sel_hi:[1,0]
	v_pk_fma_f32 v[24:25], v[140:141], v[24:25], v[150:151]
	v_pk_fma_f32 v[26:27], v[134:135], v[26:27], v[238:239]
	global_store_dwordx4 v[186:187], v[24:27], off offset:64
	s_waitcnt vmcnt(31)
	v_lshlrev_b32_e32 v148, 16, v240
	v_and_b32_e32 v149, 0xffff0000, v240
	v_lshlrev_b32_e32 v240, 16, v241
	v_and_b32_e32 v241, 0xffff0000, v241
	v_pk_mul_f32 v[148:149], v[148:149], s[90:91] op_sel_hi:[1,0]
	v_pk_mul_f32 v[240:241], v[240:241], s[90:91] op_sel_hi:[1,0]
	v_pk_fma_f32 v[20:21], v[140:141], v[20:21], v[148:149]
	v_pk_fma_f32 v[22:23], v[134:135], v[22:23], v[240:241]
	global_store_dwordx4 v[186:187], v[20:23], off offset:512
	s_waitcnt vmcnt(31)
	v_lshlrev_b32_e32 v150, 16, v242
	v_and_b32_e32 v151, 0xffff0000, v242
	v_lshlrev_b32_e32 v242, 16, v243
	v_and_b32_e32 v243, 0xffff0000, v243
	v_pk_mul_f32 v[150:151], v[150:151], s[90:91] op_sel_hi:[1,0]
	v_pk_mul_f32 v[242:243], v[242:243], s[90:91] op_sel_hi:[1,0]
	v_pk_fma_f32 v[12:13], v[140:141], v[12:13], v[150:151]
	v_pk_fma_f32 v[14:15], v[134:135], v[14:15], v[242:243]
	global_store_dwordx4 v[186:187], v[12:15], off offset:576
	s_mov_b64 s[16:17], 0xb0000
	v_lshl_add_u64 v[182:183], v[184:185], 0, s[16:17]
	s_waitcnt vmcnt(31)
	v_lshlrev_b32_e32 v148, 16, v244
	v_and_b32_e32 v149, 0xffff0000, v244
	v_lshlrev_b32_e32 v244, 16, v245
	v_and_b32_e32 v245, 0xffff0000, v245
	v_pk_mul_f32 v[148:149], v[148:149], s[90:91] op_sel_hi:[1,0]
	v_pk_mul_f32 v[244:245], v[244:245], s[90:91] op_sel_hi:[1,0]
	v_pk_fma_f32 v[16:17], v[140:141], v[16:17], v[148:149]
	v_pk_fma_f32 v[18:19], v[134:135], v[18:19], v[244:245]
	global_store_dwordx4 v[182:183], v[16:19], off
	s_waitcnt vmcnt(31)
	v_lshlrev_b32_e32 v150, 16, v246
	v_and_b32_e32 v151, 0xffff0000, v246
	v_lshlrev_b32_e32 v246, 16, v247
	v_and_b32_e32 v247, 0xffff0000, v247
	v_pk_mul_f32 v[150:151], v[150:151], s[90:91] op_sel_hi:[1,0]
	v_pk_mul_f32 v[246:247], v[246:247], s[90:91] op_sel_hi:[1,0]
	v_pk_fma_f32 v[8:9], v[140:141], v[8:9], v[150:151]
	v_pk_fma_f32 v[10:11], v[134:135], v[10:11], v[246:247]
	global_store_dwordx4 v[182:183], v[8:11], off offset:64
	s_waitcnt vmcnt(31)
	v_lshlrev_b32_e32 v148, 16, v248
	v_and_b32_e32 v149, 0xffff0000, v248
	v_lshlrev_b32_e32 v248, 16, v249
	v_and_b32_e32 v249, 0xffff0000, v249
	v_pk_mul_f32 v[148:149], v[148:149], s[90:91] op_sel_hi:[1,0]
	v_pk_mul_f32 v[248:249], v[248:249], s[90:91] op_sel_hi:[1,0]
	v_pk_fma_f32 v[4:5], v[140:141], v[4:5], v[148:149]
	v_pk_fma_f32 v[6:7], v[134:135], v[6:7], v[248:249]
	global_store_dwordx4 v[182:183], v[4:7], off offset:512
	s_waitcnt vmcnt(31)
	v_lshlrev_b32_e32 v150, 16, v250
	v_and_b32_e32 v151, 0xffff0000, v250
	v_lshlrev_b32_e32 v250, 16, v251
	v_and_b32_e32 v251, 0xffff0000, v251
	v_pk_mul_f32 v[150:151], v[150:151], s[90:91] op_sel_hi:[1,0]
	v_pk_mul_f32 v[250:251], v[250:251], s[90:91] op_sel_hi:[1,0]
	v_pk_fma_f32 v[0:1], v[140:141], v[0:1], v[150:151]
	v_pk_fma_f32 v[2:3], v[134:135], v[2:3], v[250:251]
	global_store_dwordx4 v[182:183], v[0:3], off offset:576
	s_branch .LBB0_788
